# GLA scan step: A-operand LDS reads pipelined 4 deep (fresh registers) instead of read/wait/MFMA one at a time
# speedup vs baseline: 1.0262x; 1.0006x over previous
; DI void phase_scan(int wid0, const Params& p, unsigned char* lds, bool dry) {
;     ...
;             const unsigned vao = vs_base + (unsigned)(cur * 9216 + (8 * l4 + (l15 >> 2)) * 144 + 2 * (16 * cb0 + 4 * (l15 & 3)));
;             const unsigned vau = vs_base + (unsigned)(cur * 9216 + (8 * hi + (l15 >> 2)) * 144 + 2 * (16 * ((lane >> 4) & 1) + 4 * (l15 & 3)));
;             s16x4 ol[2][2], oh[2][2], ul0[4], uh0[4], ul1[4], uh1[4];
; #pragma unroll
;             for (int cc = 0; cc < 2; ++cc)
; #pragma unroll
;                 for (int s = 0; s < 2; ++s) { ol[cc][s] = tr_read0(vao + cc * 32 + s * 32 * 144); oh[cc][s] = tr_read0(vao + cc * 32 + s * 32 * 144 + 4 * 144); }
; #pragma unroll
;             for (int s = 0; s < 2; ++s) {
;                 ul0[s] = tr_read0(vau + s * 16 * 144); uh0[s] = tr_read0(vau + s * 16 * 144 + 4 * 144);
;                 ul1[s] = tr_read0(vau + s * 16 * 144 + 64); uh1[s] = tr_read0(vau + s * 16 * 144 + 4 * 144 + 64);
;             }
;             {
;                 __builtin_amdgcn_sched_barrier(0);
;                 f32x4 oacc[2];
; #pragma unroll
;                 for (int cc = 0; cc < 2; ++cc) {
;                     const int cb = cb0 + cc; oacc[cc] = (f32x4){0.f, 0.f, 0.f, 0.f};
; #pragma unroll
;                     for (int s = 0; s < 2; ++s) oacc[cc] = MFMA16(PK8(ol[cc][s], oh[cc][s]), at[s], oacc[cc]);
;                     const bf16_t* sp = sbt + cur * 16896 + (16 * cb + l15) * 264 + 8 * l4;
; #pragma unroll
;                     for (int s = 0; s < 8; ++s) { const bf16x8 bfr = *(const bf16x8*)(sp + 32 * s); oacc[cc] = MFMA16(bfr, aq[s], oacc[cc]); }
;                 }
; #pragma unroll
;                 for (int s = 2; s < 4; ++s) {
;                     ul0[s] = tr_read0(vau + s * 16 * 144); uh0[s] = tr_read0(vau + s * 16 * 144 + 4 * 144);
;                     ul1[s] = tr_read0(vau + s * 16 * 144 + 64); uh1[s] = tr_read0(vau + s * 16 * 144 + 4 * 144 + 64);
;                 }
; #pragma unroll
;                 for (int cc = 0; cc < 2; ++cc) {
;                     const int col = colv + 16 * (cb0 + cc) + 4 * l4;
;                     u32x2 w; w.x = cvt_pk_bf16(oacc[cc][0], oacc[cc][1]); w.y = cvt_pk_bf16(oacc[cc][2], oacc[cc][3]);
;                     if (dry) {} else if (c > 0) *(u32x2*)(vb + (size_t)(row0 + i) * 2048 + col) = w;
.LBB0_232:
	s_or_b64 exec, exec, s[8:9]
	s_lshl_b32 s2, s12, 2
	s_and_b32 s2, s2, 28
	s_ashr_i32 s6, s12, 6
	s_add_i32 s8, s2, s6
	s_and_b32 s10, s6, 3
	s_lshl_b32 s2, s12, 3
	s_and_b32 s2, s2, 0x1c0
	s_lshl_b32 s6, s10, 9
	s_or_b32 s9, s6, s2
	s_lshl_b32 s2, s9, 1
	v_lshl_add_u64 v[2:3], v[128:129], 0, s[2:3]
	global_load_dwordx4 v[34:37], v[2:3], off
	s_ashr_i32 s11, s8, 2
	s_lshl_b32 s15, s11, 12
	s_mov_b32 s7, s3
	s_cmp_lt_u32 s8, 4
	v_lshl_add_u64 v[162:163], v[134:135], 0, s[6:7]
	s_cselect_b64 s[6:7], -1, 0
	s_or_b32 s8, s10, 0x800
	v_lshl_add_u64 v[176:177], v[140:141], 0, s[2:3]
	s_lshl_b32 s2, s8, 13
	v_lshl_add_u64 v[2:3], v[132:133], 0, s[2:3]
	global_load_dwordx4 v[18:21], v[2:3], off
	global_load_dwordx4 v[22:25], v[2:3], off offset:1024
	v_lshl_add_u64 v[2:3], v[162:163], 0, v[146:147]
	global_load_dwordx4 v[70:73], v[2:3], off
	v_lshl_add_u64 v[2:3], v[162:163], 0, v[148:149]
	global_load_dwordx4 v[66:69], v[2:3], off
	v_lshl_add_u64 v[2:3], v[162:163], 0, v[150:151]
	global_load_dwordx4 v[62:65], v[2:3], off
	v_lshl_add_u64 v[2:3], v[162:163], 0, v[152:153]
	global_load_dwordx4 v[58:61], v[2:3], off
	v_lshl_add_u64 v[2:3], v[162:163], 0, v[154:155]
	global_load_dwordx4 v[54:57], v[2:3], off
	v_lshl_add_u64 v[2:3], v[162:163], 0, v[156:157]
	global_load_dwordx4 v[30:33], v[2:3], off
	v_lshl_add_u64 v[2:3], v[162:163], 0, v[158:159]
	global_load_dwordx4 v[26:29], v[2:3], off
	v_lshl_add_u64 v[2:3], v[162:163], 0, v[160:161]
	s_lshl_b32 s2, s8, 15
	v_add_u32_e32 v78, s15, v126
	global_load_dwordx4 v[74:77], v[2:3], off
	v_lshl_add_u64 v[2:3], v[136:137], 0, s[2:3]
	s_lshl_b32 s2, s8, 10
	v_lshl_add_u64 v[14:15], v[138:139], 0, s[2:3]
	v_ashrrev_i32_e32 v79, 31, v78
	global_load_dwordx4 v[50:53], v[2:3], off
	global_load_dwordx4 v[46:49], v[2:3], off offset:1024
	global_load_dwordx4 v[42:45], v[2:3], off offset:2048
	global_load_dwordx4 v[38:41], v[2:3], off offset:3072
	s_nop 0
	global_load_dwordx4 v[2:5], v[14:15], off
	global_load_dwordx4 v[6:9], v[14:15], off offset:32
	global_load_dwordx4 v[10:13], v[14:15], off offset:64
	s_nop 0
	global_load_dwordx4 v[14:17], v[14:15], off offset:96
	v_or_b32_e32 v98, s9, v183
	s_and_b64 s[6:7], s[6:7], s[4:5]
	s_waitcnt vmcnt(18)
	ds_write_b128 v127, v[34:37]
	v_lshlrev_b64 v[34:35], 12, v[78:79]
	s_waitcnt lgkmcnt(0)
	s_barrier
	v_lshl_add_u64 v[34:35], v[176:177], 0, v[34:35]
	global_load_dwordx4 v[34:37], v[34:35], off
	ds_read_b64_tr_b16 v[96:97], v181 offset:576
	ds_read_b64_tr_b16 v[100:101], v181 offset:4608
	ds_read_b64_tr_b16 v[102:103], v181 offset:5184
	ds_read_b64_tr_b16 v[94:95], v181
	ds_read_b64_tr_b16 v[104:105], v181 offset:32
	ds_read_b64_tr_b16 v[106:107], v181 offset:608
	ds_read_b64_tr_b16 v[108:109], v181 offset:4640
	ds_read_b64_tr_b16 v[110:111], v181 offset:5216
	ds_read_b64_tr_b16 v[90:91], v180
	ds_read_b64_tr_b16 v[92:93], v180 offset:576
	ds_read_b64_tr_b16 v[82:83], v180 offset:64
	ds_read_b64_tr_b16 v[84:85], v180 offset:640
	ds_read_b64_tr_b16 v[86:87], v180 offset:2304
	ds_read_b64_tr_b16 v[88:89], v180 offset:2880
	ds_read_b64_tr_b16 v[78:79], v180 offset:2368
	ds_read_b64_tr_b16 v[80:81], v180 offset:2944
	s_waitcnt vmcnt(18) lgkmcnt(12)
	v_mfma_f32_16x16x32_bf16 v[94:97], v[94:97], v[18:21], 0
	v_add_u32_e32 v0, v182, v145
	s_waitcnt vmcnt(17)
	v_mfma_f32_16x16x32_bf16 v[94:97], v[100:103], v[22:25], v[94:97]
	v_add_u32_e32 v230, v182, v189
	ds_read_b128 v[214:217], v0
	s_waitcnt lgkmcnt(11)
	v_mfma_f32_16x16x32_bf16 v[18:21], v[104:107], v[18:21], 0
	s_waitcnt lgkmcnt(9)
	v_mfma_f32_16x16x32_bf16 v[18:21], v[108:111], v[22:25], v[18:21]
	ds_read_b128 v[218:221], v0 offset:64
	ds_read_b128 v[222:225], v0 offset:128
	ds_read_b128 v[226:229], v0 offset:192
	s_waitcnt vmcnt(16) lgkmcnt(3)
	v_mfma_f32_16x16x32_bf16 v[94:97], v[214:217], v[70:73], v[94:97]
	ds_read_b128 v[236:239], v0 offset:256
	s_waitcnt vmcnt(15) lgkmcnt(3)
	v_mfma_f32_16x16x32_bf16 v[94:97], v[218:221], v[66:69], v[94:97]
	ds_read_b128 v[240:243], v0 offset:320
	s_waitcnt vmcnt(14) lgkmcnt(3)
	v_mfma_f32_16x16x32_bf16 v[94:97], v[222:225], v[62:65], v[94:97]
	ds_read_b128 v[214:217], v0 offset:384
	s_waitcnt vmcnt(13) lgkmcnt(3)
	v_mfma_f32_16x16x32_bf16 v[94:97], v[226:229], v[58:61], v[94:97]
	ds_read_b128 v[100:103], v0 offset:448
	s_waitcnt vmcnt(12) lgkmcnt(3)
	v_mfma_f32_16x16x32_bf16 v[94:97], v[236:239], v[54:57], v[94:97]
	ds_read_b128 v[222:225], v230
	s_waitcnt vmcnt(11) lgkmcnt(3)
	v_mfma_f32_16x16x32_bf16 v[94:97], v[240:243], v[30:33], v[94:97]
	ds_read_b128 v[226:229], v230 offset:64
	s_waitcnt vmcnt(10) lgkmcnt(3)
	v_mfma_f32_16x16x32_bf16 v[94:97], v[214:217], v[26:29], v[94:97]
	v_add_u32_e32 v0, v182, v189
	ds_read_b128 v[236:239], v230 offset:128
	ds_read_b128 v[240:243], v230 offset:192
	s_waitcnt lgkmcnt(3)
	v_mfma_f32_16x16x32_bf16 v[18:21], v[222:225], v[70:73], v[18:21]
	v_or_b32_e32 v70, s13, v98
	ds_read_b128 v[214:217], v230 offset:256
	s_waitcnt lgkmcnt(3)
	v_mfma_f32_16x16x32_bf16 v[18:21], v[226:229], v[66:69], v[18:21]
	ds_read_b128 v[218:221], v230 offset:320
	s_waitcnt lgkmcnt(3)
	v_mfma_f32_16x16x32_bf16 v[18:21], v[236:239], v[62:65], v[18:21]
	ds_read_b128 v[222:225], v230 offset:384
	s_waitcnt lgkmcnt(3)
	v_mfma_f32_16x16x32_bf16 v[18:21], v[240:243], v[58:61], v[18:21]
	ds_read_b128 v[22:25], v230 offset:448
	s_waitcnt lgkmcnt(3)
	v_mfma_f32_16x16x32_bf16 v[18:21], v[214:217], v[54:57], v[18:21]
	s_waitcnt lgkmcnt(2)
	v_mfma_f32_16x16x32_bf16 v[18:21], v[218:221], v[30:33], v[18:21]
	s_waitcnt lgkmcnt(1)
	v_mfma_f32_16x16x32_bf16 v[18:21], v[222:225], v[26:29], v[18:21]
	ds_read_b64_tr_b16 v[62:63], v180 offset:4608
	ds_read_b64_tr_b16 v[64:65], v180 offset:5184
	ds_read_b64_tr_b16 v[58:59], v180 offset:4672
	ds_read_b64_tr_b16 v[60:61], v180 offset:5248
	ds_read_b64_tr_b16 v[66:67], v180 offset:6912
	ds_read_b64_tr_b16 v[68:69], v180 offset:7488
	ds_read_b64_tr_b16 v[54:55], v180 offset:6976
	ds_read_b64_tr_b16 v[56:57], v180 offset:7552
	s_waitcnt vmcnt(9)
	v_mfma_f32_16x16x32_bf16 v[94:97], v[100:103], v[74:77], v[94:97]
	s_waitcnt lgkmcnt(8)
	v_mfma_f32_16x16x32_bf16 v[18:21], v[22:25], v[74:77], v[18:21]
	s_and_saveexec_b64 s[8:9], s[6:7]
	s_cbranch_execz .LBB0_234
	v_lshlrev_b32_e32 v0, 1, v70
	s_nop 2
	v_cvt_pk_bf16_f32 v22, v94, v95
	v_cvt_pk_bf16_f32 v23, v96, v97
	v_lshl_add_u64 v[24:25], v[142:143], 0, v[0:1]
	global_store_dwordx2 v[24:25], v[22:23], off
